# gemm_out: the 16 x loads now issued at the very start of the tile epilogue (before the LDS staging), so their HBM latency overlaps the staging
# baseline (speedup 1.0000x reference)
; __device__ void phase_gemm_out(const Params& p, int bid, int nb, char* lds, const TileMap& tm) {
;     ...
;     for (int j = 0; j < 2; ++j)
; #pragma unroll
;       for (int i = 0; i < 2; ++i) {
;         const int rl = 64 * wm + 32 * i + l31;
;         const float rb = rbv[rl];
; #pragma unroll
;         for (int g = 0; g < 4; ++g) {
;           const f32x16& a = acc[j][i];
;           *(float4*)(stf + rl * 132 + 64 * wn + 32 * j + 8 * g + 4 * h) = make_float4(a[4 * g] * rb, a[4 * g + 1] * rb, a[4 * g + 2] * rb, a[4 * g + 3] * rb);
;         }
;       }
;     __syncthreads();
;     const int b = m0 >> 13;
;     const float* gate = ada + b * 6144 + 2048 + n0;
;     {
;       const int c32 = tid & 31, r0 = tid >> 5;
;       const float4 gt = *(const float4*)(gate + c32 * 4);
; #pragma unroll
;       for (int q = 0; q < 16; ++q) {
;         const int row = r0 + 8 * q;
;         const size_t idx = (size_t)(m0 + row) * 1024 + n0 + c32 * 4;
;         const float4 xv = *(const float4*)(p.x + idx);
.LBB0_310:
	v_add_u32_e32 v248, s45, v79
	v_or_b32_e32 v249, s0, v66
	v_lshl_add_u32 v248, v248, 10, v249
	v_lshlrev_b32_e32 v248, 2, v248
	global_load_dwordx4 v[184:187], v248, s[72:73]
	v_add_u32_e32 v248, 0x8000, v248
	global_load_dwordx4 v[188:191], v248, s[72:73]
	v_add_u32_e32 v248, 0x8000, v248
	global_load_dwordx4 v[192:195], v248, s[72:73]
	v_add_u32_e32 v248, 0x8000, v248
	global_load_dwordx4 v[196:199], v248, s[72:73]
	v_add_u32_e32 v248, 0x8000, v248
	global_load_dwordx4 v[200:203], v248, s[72:73]
	v_add_u32_e32 v248, 0x8000, v248
	global_load_dwordx4 v[204:207], v248, s[72:73]
	v_add_u32_e32 v248, 0x8000, v248
	global_load_dwordx4 v[208:211], v248, s[72:73]
	v_add_u32_e32 v248, 0x8000, v248
	global_load_dwordx4 v[212:215], v248, s[72:73]
	v_add_u32_e32 v248, 0x8000, v248
	global_load_dwordx4 v[216:219], v248, s[72:73]
	v_add_u32_e32 v248, 0x8000, v248
	global_load_dwordx4 v[220:223], v248, s[72:73]
	v_add_u32_e32 v248, 0x8000, v248
	global_load_dwordx4 v[224:227], v248, s[72:73]
	v_add_u32_e32 v248, 0x8000, v248
	global_load_dwordx4 v[228:231], v248, s[72:73]
	v_add_u32_e32 v248, 0x8000, v248
	global_load_dwordx4 v[232:235], v248, s[72:73]
	v_add_u32_e32 v248, 0x8000, v248
	global_load_dwordx4 v[236:239], v248, s[72:73]
	v_add_u32_e32 v248, 0x8000, v248
	global_load_dwordx4 v[240:243], v248, s[72:73]
	v_add_u32_e32 v248, 0x8000, v248
	global_load_dwordx4 v[244:247], v248, s[72:73]
	s_setprio 0
	ds_read_b32 v0, v80
	s_lshr_b32 s1, s44, 6
	s_mul_i32 s40, s1, 0x1800
	s_ashr_i32 s41, s40, 31
	s_lshl_b64 s[40:41], s[40:41], 2
	s_waitcnt lgkmcnt(0)
	v_pk_mul_f32 v[50:51], v[50:51], v[0:1] op_sel_hi:[1,0]
	v_pk_mul_f32 v[52:53], v[52:53], v[0:1] op_sel_hi:[1,0]
	v_pk_mul_f32 v[54:55], v[54:55], v[0:1] op_sel_hi:[1,0]
	v_pk_mul_f32 v[56:57], v[56:57], v[0:1] op_sel_hi:[1,0]
	ds_write_b128 v82, v[50:53]
	ds_write_b128 v82, v[54:57] offset:32
	v_pk_mul_f32 v[50:51], v[58:59], v[0:1] op_sel_hi:[1,0]
	v_pk_mul_f32 v[52:53], v[60:61], v[0:1] op_sel_hi:[1,0]
	ds_write_b128 v82, v[50:53] offset:64
	v_pk_mul_f32 v[50:51], v[62:63], v[0:1] op_sel_hi:[1,0]
	v_pk_mul_f32 v[52:53], v[64:65], v[0:1] op_sel_hi:[1,0]
	ds_write_b128 v82, v[50:53] offset:96
	ds_read_b32 v0, v81
	s_add_u32 s42, s92, s40
	s_addc_u32 s43, s93, s41
	s_ashr_i32 s1, s0, 31
	s_lshl_b64 s[40:41], s[0:1], 2
	s_waitcnt lgkmcnt(0)
	v_pk_mul_f32 v[34:35], v[34:35], v[0:1] op_sel_hi:[1,0]
	v_pk_mul_f32 v[36:37], v[36:37], v[0:1] op_sel_hi:[1,0]
	ds_write_b128 v82, v[34:37] offset:16896
	v_pk_mul_f32 v[34:35], v[38:39], v[0:1] op_sel_hi:[1,0]
	v_pk_mul_f32 v[36:37], v[40:41], v[0:1] op_sel_hi:[1,0]
	ds_write_b128 v82, v[34:37] offset:16928
	v_pk_mul_f32 v[34:35], v[42:43], v[0:1] op_sel_hi:[1,0]
	v_pk_mul_f32 v[36:37], v[44:45], v[0:1] op_sel_hi:[1,0]
	ds_write_b128 v82, v[34:37] offset:16960
	v_pk_mul_f32 v[34:35], v[46:47], v[0:1] op_sel_hi:[1,0]
	v_pk_mul_f32 v[36:37], v[48:49], v[0:1] op_sel_hi:[1,0]
	ds_write_b128 v82, v[34:37] offset:16992
	ds_read_b32 v0, v80
	s_add_u32 s40, s42, s40
	s_addc_u32 s41, s43, s41
	s_add_i32 s21, s21, 1
	s_waitcnt lgkmcnt(0)
	v_pk_mul_f32 v[18:19], v[18:19], v[0:1] op_sel_hi:[1,0]
	v_pk_mul_f32 v[20:21], v[20:21], v[0:1] op_sel_hi:[1,0]
	ds_write_b128 v82, v[18:21] offset:128
	v_pk_mul_f32 v[18:19], v[22:23], v[0:1] op_sel_hi:[1,0]
	v_pk_mul_f32 v[20:21], v[24:25], v[0:1] op_sel_hi:[1,0]
	ds_write_b128 v82, v[18:21] offset:160
	v_pk_mul_f32 v[18:19], v[26:27], v[0:1] op_sel_hi:[1,0]
	v_pk_mul_f32 v[20:21], v[28:29], v[0:1] op_sel_hi:[1,0]
	ds_write_b128 v82, v[18:21] offset:192
	v_pk_mul_f32 v[18:19], v[30:31], v[0:1] op_sel_hi:[1,0]
	v_pk_mul_f32 v[20:21], v[32:33], v[0:1] op_sel_hi:[1,0]
	ds_write_b128 v82, v[18:21] offset:224
	ds_read_b32 v0, v81
	s_waitcnt lgkmcnt(0)
	v_pk_mul_f32 v[2:3], v[2:3], v[0:1] op_sel_hi:[1,0]
	v_pk_mul_f32 v[4:5], v[4:5], v[0:1] op_sel_hi:[1,0]
	ds_write_b128 v82, v[2:5] offset:17024
	v_pk_mul_f32 v[2:3], v[6:7], v[0:1] op_sel_hi:[1,0]
	v_pk_mul_f32 v[4:5], v[8:9], v[0:1] op_sel_hi:[1,0]
	ds_write_b128 v82, v[2:5] offset:17056
	v_pk_mul_f32 v[2:3], v[10:11], v[0:1] op_sel_hi:[1,0]
	v_pk_mul_f32 v[4:5], v[12:13], v[0:1] op_sel_hi:[1,0]
	v_add_u32_e32 v8, s45, v79
	ds_write_b128 v82, v[2:5] offset:17088
	v_pk_mul_f32 v[2:3], v[14:15], v[0:1] op_sel_hi:[1,0]
	v_pk_mul_f32 v[4:5], v[16:17], v[0:1] op_sel_hi:[1,0]
	v_lshlrev_b32_e32 v0, 2, v66
	v_ashrrev_i32_e32 v9, 31, v8
	ds_write_b128 v82, v[2:5] offset:17120
	v_lshl_add_u64 v[2:3], s[40:41], 0, v[0:1]
	v_mov_b32_e32 v7, s1
	v_or_b32_e32 v6, s0, v66
	v_lshlrev_b64 v[4:5], 10, v[8:9]
	s_movk_i32 s0, 0x2000
	v_lshl_add_u64 v[4:5], v[4:5], 0, v[6:7]
	v_add_co_u32_e32 v2, vcc, s0, v2
	v_lshlrev_b64 v[18:19], 2, v[4:5]
	s_nop 0
	v_addc_co_u32_e32 v3, vcc, 0, v3, vcc
	s_waitcnt lgkmcnt(0)
	s_barrier
; __device__ void phase_gemm_out(const Params& p, int bid, int nb, char* lds, const TileMap& tm) {
;     ...
;       const int c32 = tid & 31, r0 = tid >> 5;
;       const float4 gt = *(const float4*)(gate + c32 * 4);
; #pragma unroll
;       for (int q = 0; q < 16; ++q) {
;         const int row = r0 + 8 * q;
;         const size_t idx = (size_t)(m0 + row) * 1024 + n0 + c32 * 4;
;         const float4 xv = *(const float4*)(p.x + idx);
;         const float4 mv = *(const float4*)(stf + row * 132 + c32 * 4);
;         *(float4*)(p.out + idx) = make_float4(ALPHA * xv.x + gt.x * mv.x, ALPHA * xv.y + gt.y * mv.y, ALPHA * xv.z + gt.z * mv.z, ALPHA * xv.w + gt.w * mv.w);
;       }
	global_load_dwordx4 v[2:5], v[2:3], off
	v_lshl_add_u64 v[10:11], s[72:73], 0, v[18:19]
	v_add_u32_e32 v14, 8, v8
	v_ashrrev_i32_e32 v15, 31, v14
	v_lshlrev_b64 v[14:15], 10, v[14:15]
	v_lshl_add_u64 v[20:21], v[14:15], 0, v[6:7]
	ds_read_b128 v[14:17], v83
	v_lshlrev_b64 v[22:23], 2, v[20:21]
	v_lshl_add_u64 v[24:25], s[90:91], 0, v[18:19]
	ds_read_b128 v[18:21], v83 offset:4224
	v_lshl_add_u64 v[26:27], s[72:73], 0, v[22:23]
	s_mov_b64 s[40:41], 0
	s_waitcnt vmcnt(0) lgkmcnt(1)
	v_pk_mul_f32 v[14:15], v[2:3], v[14:15]
	v_pk_mul_f32 v[16:17], v[4:5], v[16:17]
	s_waitcnt vmcnt(15)
	v_pk_fma_f32 v[10:11], v[184:185], s[34:35], v[14:15] op_sel_hi:[1,0,1]
	v_pk_fma_f32 v[12:13], v[186:187], s[34:35], v[16:17] op_sel_hi:[1,0,1]
	global_store_dwordx4 v[24:25], v[10:13], off
	v_add_u32_e32 v14, 16, v8
	v_ashrrev_i32_e32 v15, 31, v14
	v_lshlrev_b64 v[14:15], 10, v[14:15]
	v_lshl_add_u64 v[14:15], v[14:15], 0, v[6:7]
	s_waitcnt lgkmcnt(0)
	v_pk_mul_f32 v[18:19], v[2:3], v[18:19]
	v_pk_mul_f32 v[20:21], v[4:5], v[20:21]
	v_lshlrev_b64 v[24:25], 2, v[14:15]
	v_lshl_add_u64 v[14:15], s[90:91], 0, v[22:23]
	v_lshl_add_u64 v[16:17], s[72:73], 0, v[24:25]
	v_lshl_add_u64 v[24:25], s[90:91], 0, v[24:25]
	s_waitcnt vmcnt(15)
	v_pk_fma_f32 v[10:11], v[188:189], s[34:35], v[18:19] op_sel_hi:[1,0,1]
	v_pk_fma_f32 v[12:13], v[190:191], s[34:35], v[20:21] op_sel_hi:[1,0,1]
	global_store_dwordx4 v[14:15], v[10:13], off
	v_add_u32_e32 v14, 24, v8
	v_ashrrev_i32_e32 v15, 31, v14
	v_lshlrev_b64 v[14:15], 10, v[14:15]
	v_lshl_add_u64 v[18:19], v[14:15], 0, v[6:7]
	ds_read_b128 v[14:17], v83 offset:8448
	v_lshlrev_b64 v[22:23], 2, v[18:19]
	ds_read_b128 v[18:21], v83 offset:12672
	v_lshl_add_u64 v[26:27], s[72:73], 0, v[22:23]
	s_waitcnt lgkmcnt(1)
	v_pk_mul_f32 v[14:15], v[2:3], v[14:15]
	v_pk_mul_f32 v[16:17], v[4:5], v[16:17]
	s_waitcnt lgkmcnt(0)
	v_pk_mul_f32 v[18:19], v[2:3], v[18:19]
	v_pk_mul_f32 v[20:21], v[4:5], v[20:21]
	s_waitcnt vmcnt(15)
	v_pk_fma_f32 v[10:11], v[192:193], s[34:35], v[14:15] op_sel_hi:[1,0,1]
	v_pk_fma_f32 v[12:13], v[194:195], s[34:35], v[16:17] op_sel_hi:[1,0,1]
	global_store_dwordx4 v[24:25], v[10:13], off
	v_add_u32_e32 v14, 32, v8
	v_ashrrev_i32_e32 v15, 31, v14
	v_lshlrev_b64 v[14:15], 10, v[14:15]
	v_lshl_add_u64 v[14:15], v[14:15], 0, v[6:7]
	v_lshlrev_b64 v[24:25], 2, v[14:15]
	v_lshl_add_u64 v[14:15], s[90:91], 0, v[22:23]
	v_lshl_add_u64 v[16:17], s[72:73], 0, v[24:25]
	v_lshl_add_u64 v[24:25], s[90:91], 0, v[24:25]
	s_waitcnt vmcnt(15)
	v_pk_fma_f32 v[10:11], v[196:197], s[34:35], v[18:19] op_sel_hi:[1,0,1]
	v_pk_fma_f32 v[12:13], v[198:199], s[34:35], v[20:21] op_sel_hi:[1,0,1]
	global_store_dwordx4 v[14:15], v[10:13], off
	v_add_u32_e32 v14, 40, v8
	v_ashrrev_i32_e32 v15, 31, v14
	v_lshlrev_b64 v[14:15], 10, v[14:15]
	v_lshl_add_u64 v[18:19], v[14:15], 0, v[6:7]
	ds_read_b128 v[14:17], v83 offset:16896
	v_lshlrev_b64 v[22:23], 2, v[18:19]
	ds_read_b128 v[18:21], v83 offset:21120
	v_lshl_add_u64 v[26:27], s[72:73], 0, v[22:23]
	s_waitcnt lgkmcnt(1)
	v_pk_mul_f32 v[14:15], v[2:3], v[14:15]
	v_pk_mul_f32 v[16:17], v[4:5], v[16:17]
	s_waitcnt lgkmcnt(0)
	v_pk_mul_f32 v[18:19], v[2:3], v[18:19]
	v_pk_mul_f32 v[20:21], v[4:5], v[20:21]
	s_waitcnt vmcnt(15)
	v_pk_fma_f32 v[10:11], v[200:201], s[34:35], v[14:15] op_sel_hi:[1,0,1]
	v_pk_fma_f32 v[12:13], v[202:203], s[34:35], v[16:17] op_sel_hi:[1,0,1]
	global_store_dwordx4 v[24:25], v[10:13], off
	v_add_u32_e32 v14, 48, v8
	v_ashrrev_i32_e32 v15, 31, v14
	v_lshlrev_b64 v[14:15], 10, v[14:15]
	v_lshl_add_u64 v[14:15], v[14:15], 0, v[6:7]
	v_lshlrev_b64 v[24:25], 2, v[14:15]
	v_lshl_add_u64 v[14:15], s[90:91], 0, v[22:23]
	v_lshl_add_u64 v[16:17], s[72:73], 0, v[24:25]
	v_lshl_add_u64 v[24:25], s[90:91], 0, v[24:25]
	s_waitcnt vmcnt(15)
	v_pk_fma_f32 v[10:11], v[204:205], s[34:35], v[18:19] op_sel_hi:[1,0,1]
	v_pk_fma_f32 v[12:13], v[206:207], s[34:35], v[20:21] op_sel_hi:[1,0,1]
	global_store_dwordx4 v[14:15], v[10:13], off
	v_add_u32_e32 v14, 56, v8
	v_ashrrev_i32_e32 v15, 31, v14
	v_lshlrev_b64 v[14:15], 10, v[14:15]
	v_lshl_add_u64 v[18:19], v[14:15], 0, v[6:7]
	ds_read_b128 v[14:17], v83 offset:25344
	v_lshlrev_b64 v[22:23], 2, v[18:19]
	ds_read_b128 v[18:21], v83 offset:29568
	v_lshl_add_u64 v[26:27], s[72:73], 0, v[22:23]
	s_waitcnt lgkmcnt(1)
	v_pk_mul_f32 v[14:15], v[2:3], v[14:15]
	v_pk_mul_f32 v[16:17], v[4:5], v[16:17]
	s_waitcnt lgkmcnt(0)
	v_pk_mul_f32 v[18:19], v[2:3], v[18:19]
	v_pk_mul_f32 v[20:21], v[4:5], v[20:21]
	s_waitcnt vmcnt(15)
	v_pk_fma_f32 v[10:11], v[208:209], s[34:35], v[14:15] op_sel_hi:[1,0,1]
	v_pk_fma_f32 v[12:13], v[210:211], s[34:35], v[16:17] op_sel_hi:[1,0,1]
	global_store_dwordx4 v[24:25], v[10:13], off
	v_add_u32_e32 v14, 64, v8
	v_ashrrev_i32_e32 v15, 31, v14
	v_lshlrev_b64 v[14:15], 10, v[14:15]
	v_lshl_add_u64 v[14:15], v[14:15], 0, v[6:7]
	v_lshlrev_b64 v[24:25], 2, v[14:15]
	v_lshl_add_u64 v[14:15], s[90:91], 0, v[22:23]
	v_lshl_add_u64 v[16:17], s[72:73], 0, v[24:25]
	v_lshl_add_u64 v[24:25], s[90:91], 0, v[24:25]
	s_waitcnt vmcnt(15)
; __device__ void phase_gemm_out(const Params& p, int bid, int nb, char* lds, const TileMap& tm) {
;     ...
; #pragma unroll
;       for (int q = 0; q < 16; ++q) {
;         const int row = r0 + 8 * q;
;         const size_t idx = (size_t)(m0 + row) * 1024 + n0 + c32 * 4;
;         const float4 xv = *(const float4*)(p.x + idx);
;         const float4 mv = *(const float4*)(stf + row * 132 + c32 * 4);
;         *(float4*)(p.out + idx) = make_float4(ALPHA * xv.x + gt.x * mv.x, ALPHA * xv.y + gt.y * mv.y, ALPHA * xv.z + gt.z * mv.z, ALPHA * xv.w + gt.w * mv.w);
;       }
;     }
;     __syncthreads();
	v_pk_fma_f32 v[10:11], v[212:213], s[34:35], v[18:19] op_sel_hi:[1,0,1]
	v_pk_fma_f32 v[12:13], v[214:215], s[34:35], v[20:21] op_sel_hi:[1,0,1]
	global_store_dwordx4 v[14:15], v[10:13], off
	v_add_u32_e32 v14, 0x48, v8
	v_ashrrev_i32_e32 v15, 31, v14
	v_lshlrev_b64 v[14:15], 10, v[14:15]
	v_lshl_add_u64 v[18:19], v[14:15], 0, v[6:7]
	ds_read_b128 v[14:17], v83 offset:33792
	v_lshlrev_b64 v[22:23], 2, v[18:19]
	ds_read_b128 v[18:21], v83 offset:38016
	v_lshl_add_u64 v[26:27], s[72:73], 0, v[22:23]
	s_waitcnt lgkmcnt(1)
	v_pk_mul_f32 v[14:15], v[2:3], v[14:15]
	v_pk_mul_f32 v[16:17], v[4:5], v[16:17]
	s_waitcnt lgkmcnt(0)
	v_pk_mul_f32 v[18:19], v[2:3], v[18:19]
	v_pk_mul_f32 v[20:21], v[4:5], v[20:21]
	s_waitcnt vmcnt(15)
	v_pk_fma_f32 v[10:11], v[216:217], s[34:35], v[14:15] op_sel_hi:[1,0,1]
	v_pk_fma_f32 v[12:13], v[218:219], s[34:35], v[16:17] op_sel_hi:[1,0,1]
	global_store_dwordx4 v[24:25], v[10:13], off
	v_add_u32_e32 v14, 0x50, v8
	v_ashrrev_i32_e32 v15, 31, v14
	v_lshlrev_b64 v[14:15], 10, v[14:15]
	v_lshl_add_u64 v[14:15], v[14:15], 0, v[6:7]
	v_lshlrev_b64 v[24:25], 2, v[14:15]
	v_lshl_add_u64 v[14:15], s[90:91], 0, v[22:23]
	v_lshl_add_u64 v[16:17], s[72:73], 0, v[24:25]
	v_lshl_add_u64 v[24:25], s[90:91], 0, v[24:25]
	s_waitcnt vmcnt(15)
	v_pk_fma_f32 v[10:11], v[220:221], s[34:35], v[18:19] op_sel_hi:[1,0,1]
	v_pk_fma_f32 v[12:13], v[222:223], s[34:35], v[20:21] op_sel_hi:[1,0,1]
	global_store_dwordx4 v[14:15], v[10:13], off
	v_add_u32_e32 v14, 0x58, v8
	v_ashrrev_i32_e32 v15, 31, v14
	v_lshlrev_b64 v[14:15], 10, v[14:15]
	v_lshl_add_u64 v[18:19], v[14:15], 0, v[6:7]
	ds_read_b128 v[14:17], v83 offset:42240
	v_lshlrev_b64 v[22:23], 2, v[18:19]
	ds_read_b128 v[18:21], v83 offset:46464
	v_lshl_add_u64 v[26:27], s[72:73], 0, v[22:23]
	s_waitcnt lgkmcnt(1)
	v_pk_mul_f32 v[14:15], v[2:3], v[14:15]
	v_pk_mul_f32 v[16:17], v[4:5], v[16:17]
	s_waitcnt lgkmcnt(0)
	v_pk_mul_f32 v[18:19], v[2:3], v[18:19]
	v_pk_mul_f32 v[20:21], v[4:5], v[20:21]
	s_waitcnt vmcnt(15)
	v_pk_fma_f32 v[10:11], v[224:225], s[34:35], v[14:15] op_sel_hi:[1,0,1]
	v_pk_fma_f32 v[12:13], v[226:227], s[34:35], v[16:17] op_sel_hi:[1,0,1]
	global_store_dwordx4 v[24:25], v[10:13], off
	v_add_u32_e32 v14, 0x60, v8
	v_ashrrev_i32_e32 v15, 31, v14
	v_lshlrev_b64 v[14:15], 10, v[14:15]
	v_lshl_add_u64 v[14:15], v[14:15], 0, v[6:7]
	v_lshlrev_b64 v[24:25], 2, v[14:15]
	v_lshl_add_u64 v[14:15], s[90:91], 0, v[22:23]
	v_lshl_add_u64 v[16:17], s[72:73], 0, v[24:25]
	v_lshl_add_u64 v[24:25], s[90:91], 0, v[24:25]
	s_waitcnt vmcnt(15)
	v_pk_fma_f32 v[10:11], v[228:229], s[34:35], v[18:19] op_sel_hi:[1,0,1]
	v_pk_fma_f32 v[12:13], v[230:231], s[34:35], v[20:21] op_sel_hi:[1,0,1]
	global_store_dwordx4 v[14:15], v[10:13], off
	v_add_u32_e32 v14, 0x68, v8
	v_ashrrev_i32_e32 v15, 31, v14
	v_lshlrev_b64 v[14:15], 10, v[14:15]
	v_lshl_add_u64 v[18:19], v[14:15], 0, v[6:7]
	ds_read_b128 v[14:17], v83 offset:50688
	v_lshlrev_b64 v[22:23], 2, v[18:19]
	ds_read_b128 v[18:21], v83 offset:54912
	v_lshl_add_u64 v[26:27], s[72:73], 0, v[22:23]
	s_waitcnt lgkmcnt(1)
	v_pk_mul_f32 v[14:15], v[2:3], v[14:15]
	v_pk_mul_f32 v[16:17], v[4:5], v[16:17]
	s_waitcnt lgkmcnt(0)
	v_pk_mul_f32 v[18:19], v[2:3], v[18:19]
	v_pk_mul_f32 v[20:21], v[4:5], v[20:21]
	s_waitcnt vmcnt(15)
	v_pk_fma_f32 v[10:11], v[232:233], s[34:35], v[14:15] op_sel_hi:[1,0,1]
	v_pk_fma_f32 v[12:13], v[234:235], s[34:35], v[16:17] op_sel_hi:[1,0,1]
	global_store_dwordx4 v[24:25], v[10:13], off
	v_add_u32_e32 v14, 0x70, v8
	v_ashrrev_i32_e32 v15, 31, v14
	v_lshlrev_b64 v[14:15], 10, v[14:15]
	v_lshl_add_u64 v[14:15], v[14:15], 0, v[6:7]
	v_lshlrev_b64 v[14:15], 2, v[14:15]
	v_lshl_add_u64 v[16:17], s[90:91], 0, v[22:23]
	v_lshl_add_u64 v[22:23], s[72:73], 0, v[14:15]
	v_add_u32_e32 v8, 0x78, v8
	v_ashrrev_i32_e32 v9, 31, v8
	v_lshlrev_b64 v[8:9], 10, v[8:9]
	s_waitcnt vmcnt(15)
	v_pk_fma_f32 v[10:11], v[236:237], s[34:35], v[18:19] op_sel_hi:[1,0,1]
	v_pk_fma_f32 v[12:13], v[238:239], s[34:35], v[20:21] op_sel_hi:[1,0,1]
	global_store_dwordx4 v[16:17], v[10:13], off
	v_lshl_add_u64 v[16:17], v[8:9], 0, v[6:7]
	ds_read_b128 v[6:9], v83 offset:59136
	v_lshlrev_b64 v[18:19], 2, v[16:17]
	v_lshl_add_u64 v[20:21], s[90:91], 0, v[14:15]
	ds_read_b128 v[14:17], v83 offset:63360
	v_lshl_add_u64 v[22:23], s[72:73], 0, v[18:19]
	s_waitcnt lgkmcnt(1)
	v_pk_mul_f32 v[6:7], v[2:3], v[6:7]
	v_pk_mul_f32 v[8:9], v[4:5], v[8:9]
	s_waitcnt lgkmcnt(0)
	v_pk_mul_f32 v[2:3], v[2:3], v[14:15]
	v_pk_mul_f32 v[4:5], v[4:5], v[16:17]
	s_waitcnt vmcnt(15)
	v_pk_fma_f32 v[6:7], v[240:241], s[34:35], v[6:7] op_sel_hi:[1,0,1]
	v_pk_fma_f32 v[8:9], v[242:243], s[34:35], v[8:9] op_sel_hi:[1,0,1]
	global_store_dwordx4 v[20:21], v[6:9], off
	v_lshl_add_u64 v[10:11], s[90:91], 0, v[18:19]
	s_waitcnt vmcnt(15)
	v_pk_fma_f32 v[2:3], v[244:245], s[34:35], v[2:3] op_sel_hi:[1,0,1]
	v_pk_fma_f32 v[4:5], v[246:247], s[34:35], v[4:5] op_sel_hi:[1,0,1]
	global_store_dwordx4 v[10:11], v[2:5], off
	s_barrier
